# MLA dense attention tile: per-segment s_setprio toggles removed (12 scalar slots per tile)
# speedup vs baseline: 1.0012x; 1.0008x over previous
; #define LAS __attribute__((address_space(3)))
; __device__ __forceinline__ float fexp2(float x) { return __builtin_amdgcn_exp2f(x); }
; template <int DQK, int VAR> ...
;     constexpr int KP = DQK + 8, VP = 72;
;     f32x4 s[2][4];
;     u32x4 vfr[2][4];
; #pragma unroll
;     for (int ch = 0; ch < 2; ++ch) {
;         bf16x8 kfr[2][DQK / 32];
; #pragma unroll
;         for (int c = 0; c < 2; ++c)
; #pragma unroll
;             for (int ks = 0; ks < DQK / 32; ++ks) kfr[c][ks] = *(const LAS bf16x8*)(sK + ((ch * 2 + c) * 16 + lr) * KP + ks * 32 + lg * 8);
;         __builtin_amdgcn_sched_barrier(0);
;         __builtin_amdgcn_s_setprio(1);
; #pragma unroll
;         for (int c = 0; c < 2; ++c) {
;             s[0][ch * 2 + c] = (f32x4){sinit, sinit, sinit, sinit}; s[1][ch * 2 + c] = s[0][ch * 2 + c];
; #pragma unroll
;             for (int ks = 0; ks < DQK / 32; ++ks) {
;                 s[0][ch * 2 + c] = __builtin_amdgcn_mfma_f32_16x16x32_bf16(kfr[c][ks], qf[0][ks], s[0][ch * 2 + c], 0, 0, 0);
;                 s[1][ch * 2 + c] = __builtin_amdgcn_mfma_f32_16x16x32_bf16(kfr[c][ks], qf[1][ks], s[1][ch * 2 + c], 0, 0, 0);
;             }
;         }
;         __builtin_amdgcn_s_setprio(0);
;         __builtin_amdgcn_sched_barrier(0);
;     }
;     __builtin_amdgcn_s_setprio(0);
;     __builtin_amdgcn_sched_barrier(0);
; #pragma unroll
;     for (int kk = 0; kk < 2; ++kk)
; #pragma unroll
;         for (int dt = 0; dt < 4; ++dt) {
;             const LAS bf16_t* vp = sVt + (dt * 16 + lr) * VP + kk * 32 + lg * 4;
;             const u32x2 v0 = *(const LAS u32x2*)vp, v1 = *(const LAS u32x2*)(vp + 16);
;             vfr[kk][dt].x = v0.x; vfr[kk][dt].y = v0.y; vfr[kk][dt].z = v1.x; vfr[kk][dt].w = v1.y;
;         }
;     __builtin_amdgcn_sched_barrier(0);
; #pragma unroll
;     for (int qt = 0; qt < 2; ++qt) {
;         const int dq = qi + qt * 16 - key0 - lg * 4;
;         const LAS float* bp = sBias + (dq + 33);
;         float ps = 0.f;
; #pragma unroll
;         for (int c = 0; c < 4; ++c)
; #pragma unroll
;             for (int j = 0; j < 4; ++j) {
;                 float val = s[qt][c][j]; float pv;
;                 if (VAR == 0) pv = fexp2(val);
;                 else if (VAR == 1) { pv = fexp2(val); pv = (dq >= c * 16 + j) ? pv : 0.f; }
;                 else if (VAR == 2) { pv = fexp2(val + bp[63 - (c * 16 + j)]); }
.LBB0_424:
	s_mulk_i32 s20, 0x6000
	s_add_i32 s20, s20, 0
	v_add_u32_e32 v70, s20, v130
	v_add_u32_e32 v161, v70, v154
	ds_read_b128 v[90:93], v161
	ds_read_b128 v[86:89], v161 offset:64
	ds_read_b128 v[82:85], v161 offset:128
	ds_read_b128 v[78:81], v161 offset:3328
	ds_read_b128 v[74:77], v161 offset:3392
	ds_read_b128 v[70:73], v161 offset:3456
	v_add3_u32 v94, s20, v153, v155
	s_cmp_gt_i32 s17, s14
	s_mov_b64 s[0:1], -1
	v_add_u32_e32 v157, 0x3800, v94
	s_cbranch_scc1 .LBB0_426
	s_waitcnt lgkmcnt(5)
	v_mfma_f32_16x16x32_bf16 v[94:97], v[90:93], v[34:37], v[66:69]
	v_mfma_f32_16x16x32_bf16 v[98:101], v[90:93], v[46:49], v[66:69]
	s_waitcnt lgkmcnt(2)
	v_mfma_f32_16x16x32_bf16 v[102:105], v[78:81], v[34:37], v[66:69]
	v_mfma_f32_16x16x32_bf16 v[106:109], v[78:81], v[46:49], v[66:69]
	v_mfma_f32_16x16x32_bf16 v[94:97], v[86:89], v[38:41], v[94:97]
	v_mfma_f32_16x16x32_bf16 v[98:101], v[86:89], v[50:53], v[98:101]
	s_waitcnt lgkmcnt(1)
	v_mfma_f32_16x16x32_bf16 v[102:105], v[74:77], v[38:41], v[102:105]
	v_mfma_f32_16x16x32_bf16 v[106:109], v[74:77], v[50:53], v[106:109]
	v_mfma_f32_16x16x32_bf16 v[94:97], v[82:85], v[42:45], v[94:97]
	v_mfma_f32_16x16x32_bf16 v[98:101], v[82:85], v[54:57], v[98:101]
	s_waitcnt lgkmcnt(0)
	v_mfma_f32_16x16x32_bf16 v[102:105], v[70:73], v[42:45], v[102:105]
	v_mfma_f32_16x16x32_bf16 v[106:109], v[70:73], v[54:57], v[106:109]
	ds_read_b128 v[110:113], v161 offset:6656
	ds_read_b128 v[114:117], v161 offset:6720
	ds_read_b128 v[118:121], v161 offset:6784
	ds_read_b128 v[122:125], v161 offset:9984
	ds_read_b128 v[162:165], v161 offset:10048
	ds_read_b128 v[166:169], v161 offset:10112
	s_waitcnt lgkmcnt(5)
	v_mfma_f32_16x16x32_bf16 v[170:173], v[110:113], v[34:37], v[66:69]
	v_mfma_f32_16x16x32_bf16 v[110:113], v[110:113], v[46:49], v[66:69]
	s_waitcnt lgkmcnt(4)
	v_mfma_f32_16x16x32_bf16 v[170:173], v[114:117], v[38:41], v[170:173]
	v_mfma_f32_16x16x32_bf16 v[110:113], v[114:117], v[50:53], v[110:113]
	s_waitcnt lgkmcnt(3)
	v_mfma_f32_16x16x32_bf16 v[114:117], v[118:121], v[42:45], v[170:173]
	v_mfma_f32_16x16x32_bf16 v[110:113], v[118:121], v[54:57], v[110:113]
	s_waitcnt lgkmcnt(2)
	v_mfma_f32_16x16x32_bf16 v[118:121], v[122:125], v[34:37], v[66:69]
	v_mfma_f32_16x16x32_bf16 v[122:125], v[122:125], v[46:49], v[66:69]
	s_waitcnt lgkmcnt(1)
	v_mfma_f32_16x16x32_bf16 v[118:121], v[162:165], v[38:41], v[118:121]
	v_mfma_f32_16x16x32_bf16 v[122:125], v[162:165], v[50:53], v[122:125]
	s_waitcnt lgkmcnt(0)
	v_mfma_f32_16x16x32_bf16 v[118:121], v[166:169], v[42:45], v[118:121]
	v_mfma_f32_16x16x32_bf16 v[122:125], v[166:169], v[54:57], v[122:125]
	ds_read_b128 v[162:165], v157
	ds_read_b128 v[166:169], v157 offset:2304
	ds_read_b128 v[170:173], v157 offset:4608
	ds_read_b128 v[174:177], v157 offset:6912
	ds_read_b128 v[178:181], v157 offset:64
	ds_read_b128 v[182:185], v157 offset:2368
	ds_read_b128 v[186:189], v157 offset:4672
	ds_read_b128 v[218:221], v157 offset:6976
	v_exp_f32_e32 v191, v94
	v_exp_f32_e32 v190, v98
	v_exp_f32_e32 v201, v95
	v_exp_f32_e32 v200, v99
	v_exp_f32_e32 v215, v96
	v_exp_f32_e32 v214, v100
	v_exp_f32_e32 v223, v97
	v_exp_f32_e32 v222, v101
	v_exp_f32_e32 v225, v102
	v_exp_f32_e32 v224, v106
	v_pk_add_f32 v[94:95], v[190:191], 0 op_sel_hi:[1,0]
	v_exp_f32_e32 v231, v103
	v_exp_f32_e32 v230, v107
	v_pk_add_f32 v[94:95], v[200:201], v[94:95]
	v_exp_f32_e32 v233, v104
	v_exp_f32_e32 v232, v108
	v_pk_add_f32 v[94:95], v[214:215], v[94:95]
	v_exp_f32_e32 v235, v105
	v_exp_f32_e32 v234, v109
	v_pk_add_f32 v[94:95], v[222:223], v[94:95]
	v_exp_f32_e32 v237, v114
	v_exp_f32_e32 v236, v110
	v_pk_add_f32 v[94:95], v[94:95], v[224:225]
	v_exp_f32_e32 v239, v115
	v_pk_add_f32 v[94:95], v[230:231], v[94:95]
	v_exp_f32_e32 v238, v111
	v_exp_f32_e32 v241, v116
	v_pk_add_f32 v[94:95], v[232:233], v[94:95]
	v_exp_f32_e32 v240, v112
	v_exp_f32_e32 v243, v117
	v_pk_add_f32 v[94:95], v[234:235], v[94:95]
	v_exp_f32_e32 v242, v113
	v_exp_f32_e32 v245, v118
	v_pk_add_f32 v[94:95], v[94:95], v[236:237]
	v_exp_f32_e32 v244, v122
	v_exp_f32_e32 v247, v119
	v_exp_f32_e32 v246, v123
	v_pk_add_f32 v[94:95], v[238:239], v[94:95]
	v_exp_f32_e32 v249, v120
	v_exp_f32_e32 v248, v124
	v_pk_add_f32 v[94:95], v[240:241], v[94:95]
	v_exp_f32_e32 v203, v121
	v_pk_add_f32 v[94:95], v[242:243], v[94:95]
	v_exp_f32_e32 v202, v125
	v_pk_add_f32 v[94:95], v[94:95], v[244:245]
	s_nop 0
	v_pk_add_f32 v[94:95], v[246:247], v[94:95]
	s_nop 0
	v_pk_add_f32 v[94:95], v[248:249], v[94:95]
	s_nop 0
	v_pk_add_f32 v[144:145], v[202:203], v[94:95]
	v_cvt_pk_bf16_f32 v94, v191, v201
	v_cvt_pk_bf16_f32 v95, v215, v223
	v_cvt_pk_bf16_f32 v96, v225, v231
	v_cvt_pk_bf16_f32 v97, v233, v235
	v_cvt_pk_bf16_f32 v98, v190, v200
	v_cvt_pk_bf16_f32 v99, v214, v222
	v_cvt_pk_bf16_f32 v100, v224, v230
	v_cvt_pk_bf16_f32 v101, v232, v234
	s_mov_b64 s[0:1], 0
	s_waitcnt lgkmcnt(7)
	v_mfma_f32_16x16x32_bf16 v[30:33], v[162:165], v[94:97], v[30:33]
	v_mfma_f32_16x16x32_bf16 v[14:17], v[162:165], v[98:101], v[14:17]
	s_waitcnt lgkmcnt(6)
	v_mfma_f32_16x16x32_bf16 v[26:29], v[166:169], v[94:97], v[26:29]
	v_mfma_f32_16x16x32_bf16 v[10:13], v[166:169], v[98:101], v[10:13]
	s_waitcnt lgkmcnt(5)
	v_mfma_f32_16x16x32_bf16 v[22:25], v[170:173], v[94:97], v[22:25]
	v_mfma_f32_16x16x32_bf16 v[6:9], v[170:173], v[98:101], v[6:9]
	v_cvt_pk_bf16_f32 v170, v237, v239
	v_cvt_pk_bf16_f32 v171, v241, v243
	v_cvt_pk_bf16_f32 v172, v245, v247
	s_waitcnt lgkmcnt(4)
	v_mfma_f32_16x16x32_bf16 v[18:21], v[174:177], v[94:97], v[18:21]
	v_cvt_pk_bf16_f32 v173, v249, v203
	v_mfma_f32_16x16x32_bf16 v[2:5], v[174:177], v[98:101], v[2:5]
	v_cvt_pk_bf16_f32 v174, v236, v238
	v_cvt_pk_bf16_f32 v175, v240, v242
	v_cvt_pk_bf16_f32 v176, v244, v246
	s_waitcnt lgkmcnt(3)
	v_mfma_f32_16x16x32_bf16 v[30:33], v[178:181], v[170:173], v[30:33]
	v_cvt_pk_bf16_f32 v177, v248, v202
	s_nop 0
	v_mfma_f32_16x16x32_bf16 v[14:17], v[178:181], v[174:177], v[14:17]
	s_waitcnt lgkmcnt(2)
	v_mfma_f32_16x16x32_bf16 v[26:29], v[182:185], v[170:173], v[26:29]
	v_mfma_f32_16x16x32_bf16 v[10:13], v[182:185], v[174:177], v[10:13]
	s_waitcnt lgkmcnt(1)
	v_mfma_f32_16x16x32_bf16 v[22:25], v[186:189], v[170:173], v[22:25]
	v_mfma_f32_16x16x32_bf16 v[6:9], v[186:189], v[174:177], v[6:9]
	s_waitcnt lgkmcnt(0)
	v_mfma_f32_16x16x32_bf16 v[18:21], v[218:221], v[170:173], v[18:21]
	v_mfma_f32_16x16x32_bf16 v[2:5], v[218:221], v[174:177], v[2:5]
; #define LAS __attribute__((address_space(3)))
; __device__ __forceinline__ float fexp2(float x) { return __builtin_amdgcn_exp2f(x); }
; template <int DQK, int VAR> ...
;     constexpr int KP = DQK + 8, VP = 72;
;     f32x4 s[2][4];
;     u32x4 vfr[2][4];
; #pragma unroll
;     for (int ch = 0; ch < 2; ++ch) {
;         bf16x8 kfr[2][DQK / 32];
; #pragma unroll
;         for (int c = 0; c < 2; ++c)
; #pragma unroll
;             for (int ks = 0; ks < DQK / 32; ++ks) kfr[c][ks] = *(const LAS bf16x8*)(sK + ((ch * 2 + c) * 16 + lr) * KP + ks * 32 + lg * 8);
;         __builtin_amdgcn_sched_barrier(0);
;         __builtin_amdgcn_s_setprio(1);
; #pragma unroll
;         for (int c = 0; c < 2; ++c) {
;             s[0][ch * 2 + c] = (f32x4){sinit, sinit, sinit, sinit}; s[1][ch * 2 + c] = s[0][ch * 2 + c];
; #pragma unroll
;             for (int ks = 0; ks < DQK / 32; ++ks) {
;                 s[0][ch * 2 + c] = __builtin_amdgcn_mfma_f32_16x16x32_bf16(kfr[c][ks], qf[0][ks], s[0][ch * 2 + c], 0, 0, 0);
;                 s[1][ch * 2 + c] = __builtin_amdgcn_mfma_f32_16x16x32_bf16(kfr[c][ks], qf[1][ks], s[1][ch * 2 + c], 0, 0, 0);
;             }
;         }
;         __builtin_amdgcn_s_setprio(0);
;         __builtin_amdgcn_sched_barrier(0);
;     }
;     __builtin_amdgcn_s_setprio(0);
;     __builtin_amdgcn_sched_barrier(0);
; #pragma unroll
;     for (int kk = 0; kk < 2; ++kk)
; #pragma unroll
;         for (int dt = 0; dt < 4; ++dt) {
;             const LAS bf16_t* vp = sVt + (dt * 16 + lr) * VP + kk * 32 + lg * 4;
;             const u32x2 v0 = *(const LAS u32x2*)vp, v1 = *(const LAS u32x2*)(vp + 16);
;             vfr[kk][dt].x = v0.x; vfr[kk][dt].y = v0.y; vfr[kk][dt].z = v1.x; vfr[kk][dt].w = v1.y;
;         }
;     __builtin_amdgcn_sched_barrier(0);
; #pragma unroll
;     for (int qt = 0; qt < 2; ++qt) {
;         const int dq = qi + qt * 16 - key0 - lg * 4;
;         const LAS float* bp = sBias + (dq + 33);
;         float ps = 0.f;
; #pragma unroll
;         for (int c = 0; c < 4; ++c)
; #pragma unroll
;             for (int j = 0; j < 4; ++j) {
;                 float val = s[qt][c][j]; float pv;
;                 if (VAR == 0) pv = fexp2(val);
;                 else if (VAR == 1) { pv = fexp2(val); pv = (dq >= c * 16 + j) ? pv : 0.f; }
;                 else if (VAR == 2) { pv = fexp2(val + bp[63 - (c * 16 + j)]); }
.LBB0_426:
	s_andn2_b64 vcc, exec, s[0:1]
	s_cbranch_vccnz .LBB0_428
	s_waitcnt lgkmcnt(5)
	v_mfma_f32_16x16x32_bf16 v[94:97], v[90:93], v[34:37], v[66:69]
	v_mfma_f32_16x16x32_bf16 v[90:93], v[90:93], v[46:49], v[66:69]
	s_waitcnt lgkmcnt(4)
	v_mfma_f32_16x16x32_bf16 v[94:97], v[86:89], v[38:41], v[94:97]
	v_mfma_f32_16x16x32_bf16 v[86:89], v[86:89], v[50:53], v[90:93]
	s_waitcnt lgkmcnt(3)
	v_mfma_f32_16x16x32_bf16 v[90:93], v[82:85], v[42:45], v[94:97]
	v_mfma_f32_16x16x32_bf16 v[82:85], v[82:85], v[54:57], v[86:89]
	s_waitcnt lgkmcnt(2)
	v_mfma_f32_16x16x32_bf16 v[86:89], v[78:81], v[34:37], v[66:69]
	v_mfma_f32_16x16x32_bf16 v[78:81], v[78:81], v[46:49], v[66:69]
	s_waitcnt lgkmcnt(1)
	v_mfma_f32_16x16x32_bf16 v[86:89], v[74:77], v[38:41], v[86:89]
	v_mfma_f32_16x16x32_bf16 v[74:77], v[74:77], v[50:53], v[78:81]
	s_waitcnt lgkmcnt(0)
	v_mfma_f32_16x16x32_bf16 v[78:81], v[70:73], v[42:45], v[86:89]
	v_mfma_f32_16x16x32_bf16 v[70:73], v[70:73], v[54:57], v[74:77]
	s_nop 3
	ds_read_b128 v[74:77], v161 offset:6656
	ds_read_b128 v[86:89], v161 offset:6720
	ds_read_b128 v[94:97], v161 offset:6784
	ds_read_b128 v[98:101], v161 offset:9984
	ds_read_b128 v[102:105], v161 offset:10048
	ds_read_b128 v[106:109], v161 offset:10112
	s_waitcnt lgkmcnt(5)
	v_mfma_f32_16x16x32_bf16 v[110:113], v[74:77], v[34:37], v[66:69]
	v_mfma_f32_16x16x32_bf16 v[74:77], v[74:77], v[46:49], v[66:69]
	s_waitcnt lgkmcnt(4)
	v_mfma_f32_16x16x32_bf16 v[110:113], v[86:89], v[38:41], v[110:113]
	v_mfma_f32_16x16x32_bf16 v[74:77], v[86:89], v[50:53], v[74:77]
	s_waitcnt lgkmcnt(3)
	v_mfma_f32_16x16x32_bf16 v[86:89], v[94:97], v[42:45], v[110:113]
	v_mfma_f32_16x16x32_bf16 v[74:77], v[94:97], v[54:57], v[74:77]
	s_waitcnt lgkmcnt(2)
	v_mfma_f32_16x16x32_bf16 v[94:97], v[98:101], v[34:37], v[66:69]
	v_mfma_f32_16x16x32_bf16 v[98:101], v[98:101], v[46:49], v[66:69]
	s_waitcnt lgkmcnt(1)
	v_mfma_f32_16x16x32_bf16 v[94:97], v[102:105], v[38:41], v[94:97]
	v_mfma_f32_16x16x32_bf16 v[98:101], v[102:105], v[50:53], v[98:101]
	s_waitcnt lgkmcnt(0)
; #define LAS __attribute__((address_space(3)))
; __device__ __forceinline__ float fexp2(float x) { return __builtin_amdgcn_exp2f(x); }
; template <int DQK, int VAR> ...
;     constexpr int KP = DQK + 8, VP = 72;
;     f32x4 s[2][4];
;     u32x4 vfr[2][4];
; #pragma unroll
;     for (int ch = 0; ch < 2; ++ch) {
;         bf16x8 kfr[2][DQK / 32];
; #pragma unroll
;         for (int c = 0; c < 2; ++c)
; #pragma unroll
;             for (int ks = 0; ks < DQK / 32; ++ks) kfr[c][ks] = *(const LAS bf16x8*)(sK + ((ch * 2 + c) * 16 + lr) * KP + ks * 32 + lg * 8);
;         __builtin_amdgcn_sched_barrier(0);
;         __builtin_amdgcn_s_setprio(1);
; #pragma unroll
;         for (int c = 0; c < 2; ++c) {
;             s[0][ch * 2 + c] = (f32x4){sinit, sinit, sinit, sinit}; s[1][ch * 2 + c] = s[0][ch * 2 + c];
; #pragma unroll
;             for (int ks = 0; ks < DQK / 32; ++ks) {
;                 s[0][ch * 2 + c] = __builtin_amdgcn_mfma_f32_16x16x32_bf16(kfr[c][ks], qf[0][ks], s[0][ch * 2 + c], 0, 0, 0);
;                 s[1][ch * 2 + c] = __builtin_amdgcn_mfma_f32_16x16x32_bf16(kfr[c][ks], qf[1][ks], s[1][ch * 2 + c], 0, 0, 0);
;             }
;         }
;         __builtin_amdgcn_s_setprio(0);
;         __builtin_amdgcn_sched_barrier(0);
;     }
;     __builtin_amdgcn_s_setprio(0);
;     __builtin_amdgcn_sched_barrier(0);
; #pragma unroll
;     for (int kk = 0; kk < 2; ++kk)
; #pragma unroll
;         for (int dt = 0; dt < 4; ++dt) {
;             const LAS bf16_t* vp = sVt + (dt * 16 + lr) * VP + kk * 32 + lg * 4;
;             const u32x2 v0 = *(const LAS u32x2*)vp, v1 = *(const LAS u32x2*)(vp + 16);
;             vfr[kk][dt].x = v0.x; vfr[kk][dt].y = v0.y; vfr[kk][dt].z = v1.x; vfr[kk][dt].w = v1.y;
;         }
;     __builtin_amdgcn_sched_barrier(0);
; #pragma unroll
;     for (int qt = 0; qt < 2; ++qt) {
;         const int dq = qi + qt * 16 - key0 - lg * 4;
;         const LAS float* bp = sBias + (dq + 33);
;         float ps = 0.f;
; #pragma unroll
;         for (int c = 0; c < 4; ++c)
; #pragma unroll
;             for (int j = 0; j < 4; ++j) {
;                 float val = s[qt][c][j]; float pv;
;                 if (VAR == 0) pv = fexp2(val);
;                 else if (VAR == 1) { pv = fexp2(val); pv = (dq >= c * 16 + j) ? pv : 0.f; }
;                 else if (VAR == 2) { pv = fexp2(val + bp[63 - (c * 16 + j)]); }
	v_mfma_f32_16x16x32_bf16 v[94:97], v[106:109], v[42:45], v[94:97]
	v_mfma_f32_16x16x32_bf16 v[98:101], v[106:109], v[54:57], v[98:101]
	ds_read_b128 v[102:105], v157
	ds_read_b128 v[106:109], v157 offset:2304
	ds_read_b128 v[110:113], v157 offset:4608
	ds_read_b128 v[114:117], v157 offset:6912
	ds_read_b128 v[118:121], v157 offset:64
	ds_read_b128 v[122:125], v157 offset:2368
	ds_read_b128 v[158:161], v157 offset:4672
	ds_read_b128 v[162:165], v157 offset:6976
	v_exp_f32_e32 v144, v79
	v_exp_f32_e32 v79, v87
	v_exp_f32_e32 v90, v90
	v_exp_f32_e32 v145, v80
	v_exp_f32_e32 v80, v82
	v_exp_f32_e32 v91, v91
	v_cmp_lt_i32_e32 vcc, 32, v156
	v_exp_f32_e32 v157, v81
	v_exp_f32_e32 v81, v83
	v_cndmask_b32_e32 v79, 0, v79, vcc
	v_add_u32_e32 v177, 16, v156
	v_cmp_lt_i32_e32 vcc, -1, v156
	v_exp_f32_e32 v92, v92
	v_exp_f32_e32 v170, v75
	v_cndmask_b32_e32 v75, 0, v90, vcc
	v_cmp_lt_i32_e32 vcc, -1, v177
	v_exp_f32_e32 v82, v84
	v_exp_f32_e32 v169, v74
	v_cndmask_b32_e32 v74, 0, v80, vcc
	v_cmp_lt_i32_e32 vcc, 0, v156
	v_exp_f32_e32 v93, v93
	v_exp_f32_e32 v172, v77
	v_cndmask_b32_e32 v77, 0, v91, vcc
	v_cmp_lt_i32_e32 vcc, 0, v177
	v_exp_f32_e32 v84, v85
	v_exp_f32_e32 v171, v76
	v_cndmask_b32_e32 v76, 0, v81, vcc
	v_cmp_lt_i32_e32 vcc, 1, v156
	v_exp_f32_e32 v78, v78
	v_exp_f32_e32 v166, v86
	v_cndmask_b32_e32 v81, 0, v92, vcc
	v_cmp_lt_i32_e32 vcc, 1, v177
	v_exp_f32_e32 v86, v70
	v_exp_f32_e32 v167, v88
	v_cndmask_b32_e32 v80, 0, v82, vcc
	v_cmp_lt_i32_e32 vcc, 2, v156
	v_exp_f32_e32 v88, v71
	s_mov_b32 s0, 0x7ffffff0
	v_cndmask_b32_e32 v83, 0, v93, vcc
	v_cmp_lt_i32_e32 vcc, 2, v177
	v_exp_f32_e32 v72, v72
	v_exp_f32_e32 v73, v73
	v_cndmask_b32_e32 v82, 0, v84, vcc
	v_cmp_lt_i32_e32 vcc, 15, v156
	v_exp_f32_e32 v168, v89
	v_pk_add_f32 v[70:71], v[74:75], 0 op_sel_hi:[1,0]
	v_cndmask_b32_e32 v85, 0, v78, vcc
	v_cmp_gt_u32_e32 vcc, s0, v156
	v_pk_add_f32 v[70:71], v[76:77], v[70:71]
	v_exp_f32_e32 v94, v94
	v_cndmask_b32_e32 v84, 0, v86, vcc
	v_cmp_lt_i32_e32 vcc, 16, v156
	v_pk_add_f32 v[70:71], v[80:81], v[70:71]
	v_exp_f32_e32 v174, v99
	v_cndmask_b32_e32 v87, 0, v144, vcc
	v_cmp_lt_i32_e32 vcc, 16, v177
	v_pk_add_f32 v[70:71], v[82:83], v[70:71]
	v_exp_f32_e32 v173, v98
	v_cndmask_b32_e32 v86, 0, v88, vcc
	v_cmp_lt_i32_e32 vcc, 17, v156
	v_pk_add_f32 v[70:71], v[70:71], v[84:85]
	v_exp_f32_e32 v95, v95
	v_cndmask_b32_e32 v89, 0, v145, vcc
	v_cmp_lt_i32_e32 vcc, 17, v177
	v_exp_f32_e32 v176, v101
	v_pk_add_f32 v[70:71], v[86:87], v[70:71]
	v_cndmask_b32_e32 v88, 0, v72, vcc
	v_cmp_lt_i32_e32 vcc, 18, v156
	v_exp_f32_e32 v175, v100
	v_pk_add_f32 v[70:71], v[88:89], v[70:71]
	v_cndmask_b32_e32 v91, 0, v157, vcc
	v_cmp_lt_i32_e32 vcc, 18, v177
	v_exp_f32_e32 v96, v96
	v_exp_f32_e32 v97, v97
	v_cndmask_b32_e32 v90, 0, v73, vcc
	v_cmp_lt_i32_e32 vcc, 31, v156
	v_pk_add_f32 v[70:71], v[90:91], v[70:71]
	s_nop 0
	v_cndmask_b32_e32 v93, 0, v166, vcc
	v_cmp_lt_i32_e32 vcc, 31, v177
	s_nop 1
	v_cndmask_b32_e32 v92, 0, v169, vcc
	v_cmp_lt_i32_e32 vcc, 32, v177
	v_pk_add_f32 v[70:71], v[70:71], v[92:93]
	s_nop 0
	v_cndmask_b32_e32 v78, 0, v170, vcc
	v_cmp_lt_i32_e32 vcc, 33, v156
	v_pk_add_f32 v[70:71], v[78:79], v[70:71]
	s_nop 0
	v_cndmask_b32_e32 v99, 0, v167, vcc
	v_cmp_lt_i32_e32 vcc, 33, v177
	s_nop 1
	v_cndmask_b32_e32 v98, 0, v171, vcc
	v_cmp_lt_i32_e32 vcc, 34, v156
	v_pk_add_f32 v[70:71], v[98:99], v[70:71]
	s_nop 0
	v_cndmask_b32_e32 v101, 0, v168, vcc
	v_cmp_lt_i32_e32 vcc, 34, v177
	s_nop 1
	v_cndmask_b32_e32 v100, 0, v172, vcc
	v_cmp_lt_i32_e32 vcc, 47, v156
	v_pk_add_f32 v[70:71], v[100:101], v[70:71]
	s_nop 0
	v_cndmask_b32_e32 v167, 0, v94, vcc
	v_cmp_lt_i32_e32 vcc, 47, v177
	s_nop 1
	v_cndmask_b32_e32 v166, 0, v173, vcc
	v_cmp_lt_i32_e32 vcc, 48, v156
	v_pk_add_f32 v[70:71], v[70:71], v[166:167]
	s_nop 0
	v_cndmask_b32_e32 v169, 0, v95, vcc
	v_cmp_lt_i32_e32 vcc, 48, v177
	s_nop 1
	v_cndmask_b32_e32 v168, 0, v174, vcc
	v_cmp_lt_i32_e32 vcc, 49, v156
	v_pk_add_f32 v[70:71], v[168:169], v[70:71]
	s_nop 0
	v_cndmask_b32_e32 v171, 0, v96, vcc
	v_cmp_lt_i32_e32 vcc, 49, v177
	s_nop 1
	v_cndmask_b32_e32 v170, 0, v175, vcc
	v_cmp_lt_i32_e32 vcc, 50, v156
	v_pk_add_f32 v[70:71], v[170:171], v[70:71]
	s_nop 0
	v_cndmask_b32_e32 v173, 0, v97, vcc
	v_cmp_lt_i32_e32 vcc, 50, v177
	s_nop 1
	v_cndmask_b32_e32 v172, 0, v176, vcc
	v_pk_add_f32 v[144:145], v[172:173], v[70:71]
	v_cvt_pk_bf16_f32 v70, v75, v77
	v_cvt_pk_bf16_f32 v71, v81, v83
	v_cvt_pk_bf16_f32 v72, v85, v87
	v_cvt_pk_bf16_f32 v73, v89, v91
	v_cvt_pk_bf16_f32 v74, v74, v76
	v_cvt_pk_bf16_f32 v75, v80, v82
	v_cvt_pk_bf16_f32 v76, v84, v86
	v_cvt_pk_bf16_f32 v77, v88, v90
	s_waitcnt lgkmcnt(7)
	v_mfma_f32_16x16x32_bf16 v[30:33], v[102:105], v[70:73], v[30:33]
	v_mfma_f32_16x16x32_bf16 v[14:17], v[102:105], v[74:77], v[14:17]
	s_waitcnt lgkmcnt(6)
	v_mfma_f32_16x16x32_bf16 v[26:29], v[106:109], v[70:73], v[26:29]
	v_mfma_f32_16x16x32_bf16 v[10:13], v[106:109], v[74:77], v[10:13]
	s_waitcnt lgkmcnt(5)
	v_mfma_f32_16x16x32_bf16 v[22:25], v[110:113], v[70:73], v[22:25]
	v_mfma_f32_16x16x32_bf16 v[6:9], v[110:113], v[74:77], v[6:9]
	s_waitcnt lgkmcnt(4)
	v_mfma_f32_16x16x32_bf16 v[18:21], v[114:117], v[70:73], v[18:21]
	v_cvt_pk_bf16_f32 v70, v93, v79
	v_cvt_pk_bf16_f32 v71, v99, v101
	v_cvt_pk_bf16_f32 v72, v167, v169
	v_mfma_f32_16x16x32_bf16 v[2:5], v[114:117], v[74:77], v[2:5]
	v_cvt_pk_bf16_f32 v73, v171, v173
	v_cvt_pk_bf16_f32 v74, v92, v78
	v_cvt_pk_bf16_f32 v75, v98, v100
	v_cvt_pk_bf16_f32 v76, v166, v168
	v_cvt_pk_bf16_f32 v77, v170, v172
	s_waitcnt lgkmcnt(3)
	v_mfma_f32_16x16x32_bf16 v[30:33], v[118:121], v[70:73], v[30:33]
	v_mfma_f32_16x16x32_bf16 v[14:17], v[118:121], v[74:77], v[14:17]
	s_waitcnt lgkmcnt(2)
	v_mfma_f32_16x16x32_bf16 v[26:29], v[122:125], v[70:73], v[26:29]
	v_mfma_f32_16x16x32_bf16 v[10:13], v[122:125], v[74:77], v[10:13]
	s_waitcnt lgkmcnt(1)
	v_mfma_f32_16x16x32_bf16 v[22:25], v[158:161], v[70:73], v[22:25]
	v_mfma_f32_16x16x32_bf16 v[6:9], v[158:161], v[74:77], v[6:9]
	s_waitcnt lgkmcnt(0)
	v_mfma_f32_16x16x32_bf16 v[18:21], v[162:165], v[70:73], v[18:21]
	v_mfma_f32_16x16x32_bf16 v[2:5], v[162:165], v[74:77], v[2:5]
